# grid barrier: unused per-XCD generation update dropped from the leader path
# baseline (speedup 1.0000x reference)
.LBB0_1324:
	s_getpc_b64 s[98:99]
